# HGIN: row sums of squares staged once per workgroup in an LDS table; the 4 unit epilogues read it by ds_read instead of 8 serialized global loads each
# speedup vs baseline: 1.0045x; 1.0030x over previous
.LBB0_1150:
	s_cmp_lt_i32 s30, 9
	s_cselect_b64 s[4:5], -1, 0
	s_and_b64 s[0:1], s[4:5], s[0:1]
	s_andn2_b64 vcc, exec, s[0:1]
	s_cbranch_vccnz .LBB0_1192
	v_mbcnt_lo_u32_b32 v240, -1, 0
	v_mbcnt_hi_u32_b32 v240, -1, v240
	v_readlane_b32 s98, v254, 13
	s_nop 3
	s_and_b32 s99, s16, 7
	s_lshl_b32 s99, s99, 3
	s_bfe_u32 s100, s16, 0x30003
	s_add_i32 s99, s99, s100
	s_lshl_b32 s99, s99, 8
	s_lshl_b32 s100, s98, 5
	s_add_i32 s99, s99, s100
	v_and_b32_e32 v241, 15, v240
	v_lshrrev_b32_e32 v242, 4, v240
	v_add_u32_e32 v243, s99, v241
	v_lshlrev_b32_e32 v243, 6, v243
	v_lshl_add_u32 v243, v242, 4, v243
	s_add_u32 s100, s28, 0x100000
	s_addc_u32 s101, s29, 0
	global_load_dwordx4 v[246:249], v243, s[100:101]
	global_load_dwordx4 v[250:253], v243, s[100:101] offset:1024
	v_xor_b32_e32 v244, 16, v240
	v_lshlrev_b32_e32 v244, 2, v244
	v_xor_b32_e32 v245, 32, v240
	v_lshlrev_b32_e32 v245, 2, v245
	s_add_i32 s0, s17, -1
	s_cmp_lg_u32 s16, s0
	v_mbcnt_lo_u32_b32 v26, -1, 0
	v_mbcnt_hi_u32_b32 v26, -1, v26
	s_cbranch_scc1 .LBB0_1157
	s_lshl_b32 s0, s69, 1
	s_mov_b32 s1, 0
	s_lshl_b64 s[2:3], s[0:1], 12
	s_add_u32 s6, s96, s2
	v_readlane_b32 s7, v254, 23
	v_lshlrev_b32_e32 v0, 2, v26
	s_addc_u32 s7, s7, s3
	s_add_u32 s10, s8, s2
	s_waitcnt lgkmcnt(0)
	v_ashrrev_i32_e32 v1, 31, v0
	s_addc_u32 s11, s9, s3
	v_lshlrev_b64 v[0:1], 2, v[0:1]
	v_lshl_add_u64 v[24:25], s[10:11], 0, v[0:1]
	v_lshl_add_u64 v[2:3], s[6:7], 0, v[0:1]
	global_load_dwordx4 v[4:7], v[24:25], off
	global_load_dwordx4 v[8:11], v[2:3], off
	global_load_dwordx4 v[12:15], v[2:3], off offset:1024
	global_load_dwordx4 v[16:19], v[24:25], off offset:1024
	global_load_dwordx4 v[20:23], v[24:25], off offset:2048
	global_load_dwordx4 v[28:31], v[2:3], off offset:2048
	global_load_dwordx4 v[32:35], v[2:3], off offset:3072
	global_load_dwordx4 v[36:39], v[24:25], off offset:3072
	v_mbcnt_lo_u32_b32 v2, -1, 0
	v_mbcnt_hi_u32_b32 v2, -1, v2
	v_and_b32_e32 v24, 64, v2
	v_xor_b32_e32 v3, 16, v2
	v_add_u32_e32 v24, 64, v24
	v_xor_b32_e32 v25, 32, v2
	v_cmp_lt_i32_e32 vcc, v3, v24
	v_readlane_b32 s6, v254, 9
	v_readlane_b32 s7, v254, 10
	v_cndmask_b32_e32 v3, v2, v3, vcc
	v_cmp_lt_i32_e32 vcc, v25, v24
	v_lshlrev_b32_e32 v3, 2, v3
	s_add_u32 s2, s6, s2
	v_cndmask_b32_e32 v2, v2, v25, vcc
	v_lshlrev_b32_e32 v2, 2, v2
	s_addc_u32 s3, s7, s3
	v_cmp_eq_u32_e32 vcc, 0, v26
	s_waitcnt vmcnt(0)
	v_pk_add_f32 v[10:11], v[10:11], v[6:7]
	v_pk_add_f32 v[8:9], v[8:9], v[4:5]
	v_pk_add_f32 v[14:15], v[14:15], v[18:19]
	v_pk_add_f32 v[12:13], v[12:13], v[16:17]
	v_pk_add_f32 v[18:19], v[30:31], v[22:23]
	v_pk_add_f32 v[16:17], v[28:29], v[20:21]
	v_mul_f32_e32 v4, v9, v9
	v_mul_f32_e32 v5, v11, v11
	v_mul_f32_e32 v6, v13, v13
	v_mul_f32_e32 v7, v15, v15
	v_pk_add_f32 v[22:23], v[34:35], v[38:39]
	v_pk_add_f32 v[20:21], v[32:33], v[36:37]
	v_mul_f32_e32 v24, v17, v17
	v_mul_f32_e32 v25, v19, v19
	v_fmac_f32_e32 v4, v8, v8
	v_fmac_f32_e32 v5, v10, v10
	v_fmac_f32_e32 v6, v12, v12
	v_fmac_f32_e32 v7, v14, v14
	v_mul_f32_e32 v27, v21, v21
	v_mul_f32_e32 v28, v23, v23
	v_fmac_f32_e32 v24, v16, v16
	v_fmac_f32_e32 v25, v18, v18
	v_add_f32_e32 v4, v4, v5
	v_add_f32_e32 v5, v6, v7
	v_fmac_f32_e32 v27, v20, v20
	v_fmac_f32_e32 v28, v22, v22
	v_add_f32_e32 v6, v24, v25
	v_add_f32_e32 v4, v4, v5
	v_add_f32_e32 v4, v4, v6
	v_add_f32_e32 v5, v27, v28
	v_add_f32_e32 v4, v4, v5
	v_lshl_add_u64 v[6:7], s[2:3], 0, v[0:1]
	global_store_dwordx4 v[6:7], v[8:11], off
	global_store_dwordx4 v[6:7], v[12:15], off offset:1024
	global_store_dwordx4 v[6:7], v[16:19], off offset:2048
	global_store_dwordx4 v[6:7], v[20:23], off offset:3072
	v_add_f32_dpp v4, v4, v4 quad_perm:[1,0,3,2] row_mask:0xf bank_mask:0xf bound_ctrl:1
	s_nop 1
	v_add_f32_dpp v4, v4, v4 quad_perm:[2,3,0,1] row_mask:0xf bank_mask:0xf bound_ctrl:1
	s_nop 1
	v_add_f32_dpp v4, v4, v4 row_half_mirror row_mask:0xf bank_mask:0xf bound_ctrl:1
	s_nop 1
	v_add_f32_dpp v4, v4, v4 row_mirror row_mask:0xf bank_mask:0xf bound_ctrl:1
	ds_bpermute_b32 v5, v3, v4
	s_waitcnt lgkmcnt(0)
	v_add_f32_e32 v4, v4, v5
	ds_bpermute_b32 v5, v2, v4
	s_and_saveexec_b64 s[2:3], vcc
	s_cbranch_execz .LBB0_1154
	s_lshl_b32 s6, s0, 2
	s_waitcnt lgkmcnt(0)
	v_add_f32_e32 v4, v4, v5
	v_mov_b32_e32 v5, s6
	v_readlane_b32 s6, v254, 11
	v_readlane_b32 s7, v254, 12
	s_nop 4
	global_store_dword v5, v4, s[6:7]

.LBB0_1164:
	s_waitcnt vmcnt(0)
	v_add_f32_e32 v246, v247, v246
	v_add_f32_e32 v247, v248, v249
	v_add_f32_e32 v250, v251, v250
	v_add_f32_e32 v251, v252, v253
	v_add_f32_e32 v248, v250, v251
	v_add_f32_e32 v249, v246, v247
	ds_bpermute_b32 v253, v244, v249
	ds_bpermute_b32 v252, v244, v248
	s_waitcnt lgkmcnt(0)
	v_pk_add_f32 v[242:243], v[248:249], v[252:253]
	ds_bpermute_b32 v253, v245, v243
	ds_bpermute_b32 v252, v245, v242
	s_waitcnt lgkmcnt(0)
	v_pk_add_f32 v[242:243], v[242:243], v[252:253]
	s_lshl_b32 s99, s98, 7
	v_lshl_add_u32 v240, v241, 2, s99
	v_add_u32_e32 v240, 0x22800, v240
	ds_write_b32 v240, v243
	ds_write_b32 v240, v242 offset:64
	s_waitcnt lgkmcnt(0)
	s_cmpk_gt_i32 s16, 0x3ff
	v_readfirstlane_b32 s14, v28
	s_waitcnt vmcnt(0) lgkmcnt(0)
	s_barrier
	s_cbranch_scc1 .LBB0_1192
	s_ashr_i32 s19, s16, 31
	s_lshr_b32 s0, s19, 29
	s_add_i32 s3, s16, s0
	s_and_b32 s0, s3, -8
	s_sub_i32 s6, s16, s0
	s_cmp_gt_i32 s6, -1
	s_cbranch_scc0 .LBB0_1167
	s_lshl_b32 s2, s6, 7
	s_cbranch_execz .LBB0_1168
	s_branch .LBB0_1169

.LBB0_1184:
	v_and_b32_e32 v129, 64, v178
	v_xor_b32_e32 v128, 16, v178
	v_add_u32_e32 v129, 64, v129
	v_cmp_lt_i32_e32 vcc, v128, v129
	v_lshl_add_u32 v160, s41, 8, v172
	v_ashrrev_i32_e32 v161, 31, v160
	v_cndmask_b32_e32 v128, v178, v128, vcc
	v_lshlrev_b32_e32 v185, 2, v128
	v_xor_b32_e32 v128, 32, v178
	v_cmp_lt_i32_e32 vcc, v128, v129
	v_or_b32_e32 v162, 16, v160
	v_ashrrev_i32_e32 v163, 31, v162
	v_lshlrev_b32_e32 v240, 2, v172
	v_add_u32_e32 v240, 0x22800, v240
	v_cndmask_b32_e32 v128, v178, v128, vcc
	v_lshlrev_b32_e32 v140, 2, v128
	s_mov_b32 s2, 0x358637bd
	v_mov_b64_e32 v[166:167], s[2:3]
	v_or_b32_e32 v168, 32, v160
	v_ashrrev_i32_e32 v169, 31, v168
	v_or_b32_e32 v164, 48, v160
	v_ashrrev_i32_e32 v165, 31, v164
	v_add_u32_e32 v158, 0x80, v160
	v_ashrrev_i32_e32 v159, 31, v158
	v_add_u32_e32 v156, 0x90, v160
	v_ashrrev_i32_e32 v157, 31, v156
	s_lshl_b32 s37, s40, 8
	s_ashr_i32 s39, s40, 2
	s_nop 0
	ds_read_b32 v129, v240
	ds_read_b32 v128, v240 offset:64
	s_waitcnt lgkmcnt(0)
	v_pk_fma_f32 v[128:129], v[128:129], s[18:19], v[166:167] op_sel_hi:[1,0,0]
	s_nop 0
	v_mul_f32_e32 v130, 0x4b800000, v129
	v_cmp_gt_f32_e64 s[2:3], s91, v129
	v_cmp_gt_f32_e32 vcc, s91, v128
	s_nop 0
	v_cndmask_b32_e64 v129, v129, v130, s[2:3]
	v_rsq_f32_e32 v129, v129
	s_nop 0
	v_mul_f32_e32 v130, 0x45800000, v129
	v_cndmask_b32_e64 v184, v129, v130, s[2:3]
	v_mul_f32_e32 v129, 0x4b800000, v128
	v_cndmask_b32_e32 v128, v128, v129, vcc
	v_rsq_f32_e32 v128, v128
	v_mul_f32_e32 v239, v124, v184
	v_mul_f32_e32 v124, 0xbfb8aa3b, v239
	v_exp_f32_e32 v124, v124
	v_mul_f32_e32 v129, 0x45800000, v128
	v_cndmask_b32_e32 v183, v128, v129, vcc
	v_add_f32_e32 v124, 1.0, v124
	v_rcp_f32_e32 v194, v124
	v_mul_f32_e32 v238, v125, v184
	v_mul_f32_e32 v237, v126, v184
	v_mul_f32_e32 v236, v127, v184
	v_mul_f32_e32 v235, v120, v184
	v_mul_f32_e32 v234, v121, v184
	v_mul_f32_e32 v233, v122, v184
	v_mul_f32_e32 v232, v123, v184
	v_mul_f32_e32 v231, v108, v184
	v_mul_f32_e32 v230, v109, v184
	v_mul_f32_e32 v229, v110, v184
	v_mul_f32_e32 v228, v111, v184
	v_mul_f32_e32 v227, v104, v184
	v_mul_f32_e32 v226, v105, v184
	v_mul_f32_e32 v225, v106, v184
	v_mul_f32_e32 v224, v107, v184
	v_mul_f32_e32 v223, v116, v183
	v_mul_f32_e32 v222, v117, v183
	v_mul_f32_e32 v221, v118, v183
	v_mul_f32_e32 v220, v119, v183
	v_mul_f32_e32 v219, v112, v183
	v_mul_f32_e32 v218, v113, v183
	v_mul_f32_e32 v217, v114, v183
	v_mul_f32_e32 v216, v115, v183
	v_mul_f32_e32 v214, v92, v183
	v_mul_f32_e32 v213, v93, v183
	v_mul_f32_e32 v212, v94, v183
	v_mul_f32_e32 v211, v95, v183
	v_mul_f32_e32 v210, v88, v183
	v_mul_f32_e32 v209, v89, v183
	v_mul_f32_e32 v208, v90, v183
	v_mul_f32_e32 v207, v91, v183
	v_lshlrev_b64 v[104:105], 11, v[162:163]
	v_lshlrev_b64 v[88:89], 11, v[168:169]
	v_mul_f32_e32 v192, 0xbfb8aa3b, v238
	v_mul_f32_e32 v191, 0xbfb8aa3b, v237
	v_mul_f32_e32 v193, 0xbfb8aa3b, v235
	v_mul_f32_e32 v188, 0xbfb8aa3b, v234
	v_mul_f32_e32 v190, 0xbfb8aa3b, v233
	v_mul_f32_e32 v117, 0xbfb8aa3b, v231
	v_mul_f32_e32 v115, 0xbfb8aa3b, v230
	v_mul_f32_e32 v113, 0xbfb8aa3b, v229
	v_mul_f32_e32 v111, 0xbfb8aa3b, v228
	v_mul_f32_e32 v116, 0xbfb8aa3b, v227
	v_mul_f32_e32 v114, 0xbfb8aa3b, v226
	v_mul_f32_e32 v112, 0xbfb8aa3b, v225
	v_mul_f32_e32 v110, 0xbfb8aa3b, v224
	v_mul_f32_e32 v184, 0xbfb8aa3b, v223
	v_mul_f32_e32 v169, 0xbfb8aa3b, v221
	v_mul_f32_e32 v183, 0xbfb8aa3b, v219
	v_mul_f32_e32 v168, 0xbfb8aa3b, v217
	v_mul_f32_e32 v109, 0xbfb8aa3b, v214
	v_mul_f32_e32 v107, 0xbfb8aa3b, v213
	v_mul_f32_e32 v108, 0xbfb8aa3b, v210
	v_mul_f32_e32 v106, 0xbfb8aa3b, v209
	s_nop 0
	ds_read_b32 v129, v240 offset:128
	ds_read_b32 v128, v240 offset:192
	s_waitcnt lgkmcnt(0)
	v_pk_fma_f32 v[128:129], v[128:129], s[18:19], v[166:167] op_sel_hi:[1,0,0]
	s_nop 0
	v_mul_f32_e32 v130, 0x4b800000, v129
	v_cmp_gt_f32_e64 s[2:3], s91, v129
	v_cmp_gt_f32_e32 vcc, s91, v128
	s_nop 0
	v_cndmask_b32_e64 v129, v129, v130, s[2:3]
	v_rsq_f32_e32 v129, v129
	s_nop 0
	v_mul_f32_e32 v130, 0x45800000, v129
	v_cndmask_b32_e64 v215, v129, v130, s[2:3]
	v_mul_f32_e32 v129, 0x4b800000, v128
	v_cndmask_b32_e32 v128, v128, v129, vcc
	v_rsq_f32_e32 v128, v128
	v_mul_f32_e32 v206, v100, v215
	v_mul_f32_e32 v205, v101, v215
	v_mul_f32_e32 v204, v102, v215
	v_mul_f32_e32 v129, 0x45800000, v128
	v_cndmask_b32_e32 v182, v128, v129, vcc
	v_mul_f32_e32 v203, v103, v215
	v_mul_f32_e32 v202, v96, v215
	v_mul_f32_e32 v201, v97, v215
	v_mul_f32_e32 v200, v98, v215
	v_mul_f32_e32 v199, v99, v215
	v_mul_f32_e32 v198, v84, v215
	v_mul_f32_e32 v197, v85, v215
	v_mul_f32_e32 v196, v86, v215
	v_mul_f32_e32 v195, v87, v215
	v_mul_f32_e32 v189, v72, v215
	v_mul_f32_e32 v73, v73, v215
	v_mul_f32_e32 v72, v74, v215
	v_mul_f32_e32 v103, 0xbfb8aa3b, v212
	v_mul_f32_e32 v101, 0xbfb8aa3b, v211
	v_mul_f32_e32 v102, 0xbfb8aa3b, v208
	v_mul_f32_e32 v100, 0xbfb8aa3b, v207
	v_mul_f32_e32 v163, 0xbfb8aa3b, v206
	v_mul_f32_e32 v127, 0xbfb8aa3b, v204
	v_mul_f32_e32 v125, 0xbfb8aa3b, v203
	v_mul_f32_e32 v162, 0xbfb8aa3b, v202
	v_mul_f32_e32 v126, 0xbfb8aa3b, v200
	v_mul_f32_e32 v124, 0xbfb8aa3b, v199
	v_mul_f32_e32 v99, 0xbfb8aa3b, v198
	v_mul_f32_e32 v97, 0xbfb8aa3b, v197
	v_mul_f32_e32 v95, 0xbfb8aa3b, v196
	v_mul_f32_e32 v93, 0xbfb8aa3b, v195
	v_mul_f32_e32 v98, 0xbfb8aa3b, v189
	v_mul_f32_e32 v96, 0xbfb8aa3b, v73
	v_mul_f32_e32 v94, 0xbfb8aa3b, v72
	v_mul_f32_e32 v92, v75, v215
	v_lshlrev_b64 v[84:85], 11, v[164:165]
	v_mul_f32_e32 v123, v80, v182
	v_mul_f32_e32 v121, v81, v182
	v_mul_f32_e32 v119, v82, v182
	v_mul_f32_e32 v83, v83, v182
	v_mul_f32_e32 v122, v76, v182
	v_mul_f32_e32 v120, v77, v182
	v_mul_f32_e32 v118, v78, v182
	v_mul_f32_e32 v82, v79, v182
	v_mul_f32_e32 v91, v68, v182
	v_mul_f32_e32 v90, v69, v182
	v_mul_f32_e32 v87, v70, v182
	v_mul_f32_e32 v86, v71, v182
	v_mul_f32_e32 v32, v32, v182
	v_add_u32_e32 v154, 0xa0, v160
	v_ashrrev_i32_e32 v155, 31, v154
	s_nop 0
	ds_read_b32 v129, v240 offset:512
	ds_read_b32 v128, v240 offset:576
	s_waitcnt lgkmcnt(0)
	v_pk_fma_f32 v[128:129], v[128:129], s[18:19], v[166:167] op_sel_hi:[1,0,0]
	s_nop 0
	v_mul_f32_e32 v130, 0x4b800000, v129
	v_cmp_gt_f32_e64 s[2:3], s91, v129
	v_cmp_gt_f32_e32 vcc, s91, v128
	s_nop 0
	v_cndmask_b32_e64 v129, v129, v130, s[2:3]
	v_rsq_f32_e32 v129, v129
	s_nop 0
	v_mul_f32_e32 v130, 0x45800000, v129
	v_cndmask_b32_e64 v181, v129, v130, s[2:3]
	v_mul_f32_e32 v129, 0x4b800000, v128
	v_cndmask_b32_e32 v128, v128, v129, vcc
	v_rsq_f32_e32 v128, v128
	s_nop 0
	v_mul_f32_e32 v129, 0x45800000, v128
	v_cndmask_b32_e32 v180, v128, v129, vcc
	v_add_u32_e32 v152, 0xb0, v160
	v_ashrrev_i32_e32 v153, 31, v152
	v_mul_f32_e32 v186, 0xbfb8aa3b, v236
	v_mul_f32_e32 v185, 0xbfb8aa3b, v232
	v_mul_f32_e32 v171, 0xbfb8aa3b, v222
	v_mul_f32_e32 v170, 0xbfb8aa3b, v218
	s_nop 0
	ds_read_b32 v129, v240 offset:640
	ds_read_b32 v128, v240 offset:704
	s_waitcnt lgkmcnt(0)
	v_pk_fma_f32 v[128:129], v[128:129], s[18:19], v[166:167] op_sel_hi:[1,0,0]
	v_mul_f32_e32 v167, 0xbfb8aa3b, v220
	v_mul_f32_e32 v130, 0x4b800000, v129
	v_cmp_gt_f32_e64 s[2:3], s91, v129
	v_cmp_gt_f32_e32 vcc, s91, v128
	v_mul_f32_e32 v166, 0xbfb8aa3b, v216
	v_cndmask_b32_e64 v129, v129, v130, s[2:3]
	v_rsq_f32_e32 v129, v129
	s_nop 0
	v_mul_f32_e32 v130, 0x45800000, v129
	v_cndmask_b32_e64 v131, v129, v130, s[2:3]
	v_mul_f32_e32 v129, 0x4b800000, v128
	v_cndmask_b32_e32 v128, v128, v129, vcc
	v_rsq_f32_e32 v128, v128
	s_and_b32 s2, s37, 0x300
	v_or_b32_e32 v187, s2, v174
	s_cmp_lg_u32 s39, 1
	v_mul_f32_e32 v129, 0x45800000, v128
	v_cndmask_b32_e32 v130, v128, v129, vcc
	s_mov_b64 s[2:3], -1
	v_lshlrev_b32_e32 v140, 1, v187
	v_lshlrev_b64 v[128:129], 11, v[160:161]
	v_mul_f32_e32 v161, 0xbfb8aa3b, v205
	v_mul_f32_e32 v160, 0xbfb8aa3b, v201
	s_cbranch_scc1 .LBB0_1187
	s_andn2_b64 vcc, exec, s[2:3]
	s_cbranch_vccz .LBB0_1188
